# neighbourhood attention: selection-matrix row-sum MFMAs alternate between two 4-register accumulators, summed at unit end; on top of the diff two-accumulator version
# baseline (speedup 1.0000x reference)
.Lna_547:
	v_exp_f32_e32 v15, v144
	v_exp_f32_e32 v144, v128
	v_exp_f32_e32 v128, v145
	v_exp_f32_e32 v129, v129
	v_exp_f32_e32 v145, v146
	v_exp_f32_e32 v130, v130
	v_exp_f32_e32 v146, v147
	v_exp_f32_e32 v131, v131
	v_exp_f32_e32 v147, v148
	v_exp_f32_e32 v148, v132
	v_exp_f32_e32 v149, v149
	v_exp_f32_e32 v218, v133
	v_exp_f32_e32 v150, v150
	v_exp_f32_e32 v219, v134
	v_exp_f32_e32 v151, v151
	v_exp_f32_e32 v220, v135
	v_exp_f32_e32 v132, v152
	v_exp_f32_e32 v133, v136
	v_exp_f32_e32 v134, v153
	v_exp_f32_e32 v135, v137
	v_exp_f32_e32 v137, v154
	v_exp_f32_e32 v138, v138
	v_exp_f32_e32 v152, v155
	v_exp_f32_e32 v139, v139
	v_exp_f32_e32 v153, v156
	v_exp_f32_e32 v154, v140
	v_exp_f32_e32 v155, v157
	v_exp_f32_e32 v156, v141
	v_exp_f32_e32 v157, v158
	v_exp_f32_e32 v158, v142
	v_exp_f32_e32 v159, v159
	v_exp_f32_e32 v143, v143
	v_cvt_pk_bf16_f32 v128, v15, v128
	v_cvt_pk_bf16_f32 v132, v132, v134
	v_cvt_pk_bf16_f32 v136, v144, v129
	v_cvt_pk_bf16_f32 v140, v133, v135
	v_cvt_pk_bf16_f32 v129, v145, v146
	v_cvt_pk_bf16_f32 v133, v137, v152
	v_cvt_pk_bf16_f32 v137, v130, v131
	v_cvt_pk_bf16_f32 v141, v138, v139
	v_cvt_pk_bf16_f32 v130, v147, v149
	v_cvt_pk_bf16_f32 v134, v153, v155
	v_cvt_pk_bf16_f32 v138, v148, v218
	v_cvt_pk_bf16_f32 v142, v154, v156
	v_cvt_pk_bf16_f32 v131, v150, v151
	v_cvt_pk_bf16_f32 v135, v157, v159
	v_cvt_pk_bf16_f32 v139, v219, v220
	v_cvt_pk_bf16_f32 v143, v158, v143
	ds_read_b64_tr_b16 v[144:145], v0 offset:12288
	ds_read_b64_tr_b16 v[146:147], v0 offset:12800
	ds_read_b64_tr_b16 v[148:149], v0 offset:13312
	ds_read_b64_tr_b16 v[150:151], v0 offset:13824
	ds_read_b64_tr_b16 v[152:153], v0 offset:14336
	ds_read_b64_tr_b16 v[154:155], v0 offset:14848
	ds_read_b64_tr_b16 v[156:157], v0 offset:15360
	ds_read_b64_tr_b16 v[158:159], v0 offset:15872
	s_setprio 1
	s_waitcnt lgkmcnt(8)
	v_mfma_f32_32x32x16_bf16 v[16:31], v[192:195], v[128:131], v[16:31]
	v_mfma_f32_32x32x16_bf16 v[16:31], v[10:13], v[132:135], v[16:31]
	v_mfma_f32_32x32x16_bf16 v[16:31], v[6:9], v[136:139], v[16:31]
	v_mfma_f32_32x32x16_bf16 v[16:31], v[2:5], v[140:143], v[16:31]
	v_mfma_f32_16x16x32_bf16 v[48:51], v[116:119], v[128:131], v[48:51]
	s_waitcnt lgkmcnt(6)
	v_mfma_f32_32x32x16_bf16 v[32:47], v[144:147], v[128:131], v[32:47]
	v_mfma_f32_16x16x32_bf16 v[52:55], v[116:119], v[132:135], v[52:55]
	s_waitcnt lgkmcnt(4)
	v_mfma_f32_32x32x16_bf16 v[32:47], v[148:151], v[132:135], v[32:47]
	v_mfma_f32_16x16x32_bf16 v[48:51], v[116:119], v[136:139], v[48:51]
	s_waitcnt lgkmcnt(2)
	v_mfma_f32_32x32x16_bf16 v[32:47], v[152:155], v[136:139], v[32:47]
	v_mfma_f32_16x16x32_bf16 v[52:55], v[116:119], v[140:143], v[52:55]
	s_waitcnt lgkmcnt(0)
	v_mfma_f32_32x32x16_bf16 v[32:47], v[156:159], v[140:143], v[32:47]
	s_setprio 0
	s_branch .Lna_next

.Lna_541:
	v_exp_f32_e32 v0, v14
	v_exp_f32_e32 v14, v15
	v_exp_f32_e32 v15, v80
	v_exp_f32_e32 v81, v81
	v_exp_f32_e32 v82, v82
	v_exp_f32_e32 v83, v83
	v_exp_f32_e32 v94, v84
	v_exp_f32_e32 v95, v85
	v_exp_f32_e32 v84, v86
	v_exp_f32_e32 v85, v87
	v_exp_f32_e32 v86, v88
	v_exp_f32_e32 v87, v89
	v_exp_f32_e32 v88, v90
	v_exp_f32_e32 v89, v91
	v_exp_f32_e32 v90, v92
	v_exp_f32_e32 v91, v93
	v_cvt_pk_bf16_f32 v80, v0, v14
	v_cvt_pk_bf16_f32 v84, v84, v85
	v_cvt_pk_bf16_f32 v81, v15, v81
	v_cvt_pk_bf16_f32 v85, v86, v87
	v_cvt_pk_bf16_f32 v82, v82, v83
	v_cvt_pk_bf16_f32 v86, v88, v89
	v_cvt_pk_bf16_f32 v83, v94, v95
	v_cvt_pk_bf16_f32 v87, v90, v91
	s_setprio 1
	s_waitcnt lgkmcnt(0)
	v_mfma_f32_32x32x16_bf16 v[32:47], v[10:13], v[80:83], v[32:47]
	v_mfma_f32_32x32x16_bf16 v[32:47], v[6:9], v[84:87], v[32:47]
	v_mfma_f32_32x32x16_bf16 v[16:31], v[96:99], v[80:83], v[16:31]
	v_mfma_f32_16x16x32_bf16 v[48:51], v[116:119], v[80:83], v[48:51]
	v_mfma_f32_16x16x32_bf16 v[52:55], v[116:119], v[84:87], v[52:55]
	v_mfma_f32_32x32x16_bf16 v[16:31], v[2:5], v[84:87], v[16:31]
	s_setprio 0
.Lna_next:
	s_add_i32 s83, s83, 1
	s_addk_i32 s51, 0x4000
	s_add_i32 s50, s50, 64
	s_add_i32 s0, s86, s83
	s_cmp_lg_u32 s0, 2
	s_cbranch_scc1 .LBB0_528
	s_nop 15
	v_mov_b64_e32 v[80:81], v[16:17]
	v_mov_b64_e32 v[82:83], v[18:19]
	v_mov_b64_e32 v[84:85], v[20:21]
	v_mov_b64_e32 v[86:87], v[22:23]
	v_mov_b64_e32 v[88:89], v[24:25]
	v_mov_b64_e32 v[90:91], v[26:27]
	v_mov_b64_e32 v[92:93], v[28:29]
	v_mov_b64_e32 v[94:95], v[30:31]
	v_mov_b64_e32 v[96:97], v[32:33]
	v_mov_b64_e32 v[98:99], v[34:35]
	v_mov_b64_e32 v[100:101], v[36:37]
	v_mov_b64_e32 v[102:103], v[38:39]
	v_mov_b64_e32 v[104:105], v[40:41]
	v_mov_b64_e32 v[106:107], v[42:43]
	v_mov_b64_e32 v[108:109], v[44:45]
	v_mov_b64_e32 v[110:111], v[46:47]
	v_add_f32_e32 v160, v48, v52
	s_branch .LBB0_489
	s_nop 0
